# M2 prep queue rotated so the long bias / pad items are dequeued first instead of last
# baseline (speedup 1.0000x reference)
.LBB0_861:
	s_or_b64 exec, exec, s[28:29]
	v_mov_b32_e32 v0, s71
	s_waitcnt lgkmcnt(0)
	s_barrier
	ds_read_b32 v0, v0
	s_mov_b64 s[6:7], -1
	s_waitcnt lgkmcnt(0)
	v_cmp_le_i32_e32 vcc, s22, v0
	v_readfirstlane_b32 s24, v0
	s_cbranch_vccnz .LBB0_856
	s_cmpk_gt_i32 s24, 0x5f
	s_cbranch_scc0 .LBB0_1256
	s_cmpk_gt_u32 s24, 0x35f
	s_cbranch_scc0 .LBB0_1057
	s_cmpk_gt_u32 s24, 0x95f
	s_cbranch_scc0 .LBB0_1052
	s_cmpk_lt_u32 s24, 0x971
	s_cselect_b32 s25, 0x49b, 0
	s_add_i32 s24, s24, s25
	s_sub_i32 s24, s24, 17
	s_lshl_b32 s25, s24, 3
	s_cmpk_gt_u32 s24, 0xd9b
	s_cbranch_scc0 .LBB0_925
	v_mov_b32_e32 v8, v203
	s_nop 0
	v_readfirstlane_b32 s36, v8
	s_ashr_i32 s10, s36, 6
	s_add_i32 s27, s25, s10
	s_addk_i32 s27, 0x9320
	s_cmpk_gt_i32 s27, 0x2f7
	s_cbranch_scc1 .LBB0_924
	s_mul_i32 s6, s10, 0x2100
	s_add_i32 s26, s6, 0
	v_and_b32_e32 v10, 63, v8
	s_cmp_gt_i32 s27, 47
	s_mov_b64 s[6:7], -1
	s_cbranch_scc0 .LBB0_898
	s_cmpk_gt_u32 s27, 0x5f
	s_cbranch_scc0 .LBB0_895
	s_cmpk_gt_u32 s27, 0x15f
	s_cbranch_scc0 .LBB0_892
	s_cmpk_gt_u32 s27, 0x25f
	s_cbranch_scc0 .LBB0_889
	s_cmpk_gt_u32 s27, 0x267
	s_cbranch_scc0 .LBB0_886
	s_cmpk_gt_u32 s27, 0x26f
	s_cbranch_scc0 .LBB0_883
	s_cmpk_gt_u32 s27, 0x2ef
	s_cbranch_scc0 .LBB0_877
	s_lshl_b32 s6, s24, 9
	s_lshl_b32 s7, s10, 6
	s_add_i32 s6, s6, s7
	s_add_i32 s7, s6, 0xffe40a00
	s_add_i32 s6, s6, 0xffe40c00
	v_or_b32_e32 v0, s7, v10
	v_or_b32_e32 v6, s6, v10
	v_readlane_b32 s6, v248, 5
	v_mov_b32_e32 v2, v1
	v_ashrrev_i32_e32 v7, 31, v6
	v_readlane_b32 s7, v248, 6
	s_mov_b64 s[28:29], 0
	v_mov_b32_e32 v3, v2
	v_mov_b32_e32 v4, v2
	v_mov_b32_e32 v5, v2
	v_lshl_add_u64 v[6:7], v[6:7], 4, s[6:7]
	s_mov_b64 s[10:11], 0x2000
